# rglru scan-output segment: gelu computed with packed f32 ops, simpler store addressing (bit-identical) on v19
# speedup vs baseline: 1.0071x; 1.0071x over previous
; #define LAS __attribute__((address_space(3)))
; __device__ __forceinline__ unsigned f2bf(float f) { unsigned u = __builtin_bit_cast(unsigned, f); return (u + 0x7fffu + ((u >> 16) & 1u)) >> 16; }
; __device__ __forceinline__ float fgelu_tanh(float x) { const float y = 0.7978845608028654f * (x + 0.044715f * x * x * x); const float t = 1.0f - 2.0f * __builtin_amdgcn_rcpf(__builtin_amdgcn_exp2f(2.8853900817779268f * y) + 1.0f); return 0.5f * x * (1.0f + t); }
; __device__ __forceinline__ void rglru_unit(LAS unsigned char* lds, int unit, const bf16* PBp, bf16* MGp, float* SSQRp, const float* cw, const float* cbias, const float* wa, const float* ba, const float* wx, const float* bxp, const float* lam) {
;     ...
;         float h = HIN[sc];
;         { typedef float f32x2v __attribute__((ext_vector_type(2))); f32x2v pe[15];
; #pragma unroll
;           for (int s2 = 0; s2 < 15; ++s2) pe[s2] = *(const LAS f32x2v*)(PE + (s2 * 32 + sc) * 2);
; #pragma unroll
;           for (int s2 = 0; s2 < 15; ++s2) h = (s2 < ss) ? fmaf(pe[s2].x, h, pe[s2].y) : h; }
;         bf16* orow = MGp + (rowb + t0 + ss * 8) * DM + 512 + g * 64 + hf * 32 + sc;
; #pragma unroll
;         for (int k = 0; k < 8; ++k) { h = av[k] * h + uv[k]; const float gbf = __uint_as_float((unsigned)GBL[(ss * 8 + k) * 32 + sc] << 16); const unsigned yb = f2bf(h * fgelu_tanh(gbf)); orow[(size_t)k * DM] = (bf16)yb;
;             const float yf = __uint_as_float(yb << 16); YSQ[(ss * 8 + k) * 33 + sc] = yf * yf; }
.LBB0_454:
	s_or_b64 exec, exec, s[2:3]
	s_waitcnt lgkmcnt(6)
	v_fma_f32 v96, v96, v1, v97
	v_cndmask_b32_e64 v1, v1, v96, s[10:11]
	v_fmac_f32_e32 v99, v98, v1
	v_cndmask_b32_e64 v1, v1, v99, s[12:13]
	s_waitcnt lgkmcnt(5)
	v_fma_f32 v92, v92, v1, v93
	v_cndmask_b32_e64 v1, v1, v92, s[14:15]
	v_fmac_f32_e32 v95, v94, v1
	v_cndmask_b32_e64 v1, v1, v95, s[16:17]
	s_waitcnt lgkmcnt(4)
	v_fma_f32 v88, v88, v1, v89
	v_cndmask_b32_e64 v1, v1, v88, s[18:19]
	v_fmac_f32_e32 v91, v90, v1
	v_cndmask_b32_e64 v1, v1, v91, s[20:21]
	s_waitcnt lgkmcnt(3)
	v_fma_f32 v84, v84, v1, v85
	v_cndmask_b32_e64 v1, v1, v84, s[22:23]
	v_fmac_f32_e32 v87, v86, v1
	v_cndmask_b32_e64 v1, v1, v87, s[24:25]
	s_waitcnt lgkmcnt(2)
	v_fma_f32 v80, v80, v1, v81
	v_cndmask_b32_e64 v1, v1, v80, s[26:27]
	v_fmac_f32_e32 v83, v82, v1
	v_cndmask_b32_e64 v1, v1, v83, s[28:29]
	s_waitcnt lgkmcnt(1)
	v_fma_f32 v76, v76, v1, v77
	v_cndmask_b32_e64 v1, v1, v76, s[30:31]
	v_fmac_f32_e32 v79, v78, v1
	v_add_u32_e32 v76, v137, v141
	v_cndmask_b32_e64 v1, v1, v79, s[34:35]
	ds_read_u16 v76, v76
	ds_read_u16 v77, v145
	ds_read_u16 v78, v147
	ds_read_u16 v79, v148
	ds_read_u16 v80, v149
	ds_read_u16 v81, v150
	ds_read_u16 v82, v151
	ds_read_u16 v83, v152
	s_waitcnt lgkmcnt(8)
	v_fma_f32 v72, v72, v1, v73
	v_cndmask_b32_e64 v1, v1, v72, s[36:37]
	v_fmac_f32_e32 v75, v74, v1
	v_mov_b32_e32 v84, 0x3d372713
	v_cndmask_b32_e64 v1, v1, v75, s[38:39]
	v_mov_b32_e32 v86, 0x3f4c422a
	v_mov_b32_e32 v88, 0x4038aa3b
	v_mov_b32_e32 v90, 1.0
	v_mov_b32_e32 v92, -2.0
	v_mov_b32_e32 v94, 0.5
	s_waitcnt lgkmcnt(0)
	v_lshlrev_b32_e32 v76, 16, v76
	v_lshlrev_b32_e32 v77, 16, v77
	v_lshlrev_b32_e32 v78, 16, v78
	v_lshlrev_b32_e32 v79, 16, v79
	v_lshlrev_b32_e32 v80, 16, v80
	v_lshlrev_b32_e32 v81, 16, v81
	v_lshlrev_b32_e32 v82, 16, v82
	v_lshlrev_b32_e32 v83, 16, v83
	v_pk_mul_f32 v[96:97], v[76:77], v[84:85] op_sel_hi:[1,0]
	v_pk_mul_f32 v[96:97], v[96:97], v[76:77]
	v_pk_fma_f32 v[96:97], v[96:97], v[76:77], v[76:77]
	v_pk_mul_f32 v[96:97], v[96:97], v[86:87] op_sel_hi:[1,0]
	v_pk_mul_f32 v[96:97], v[96:97], v[88:89] op_sel_hi:[1,0]
	v_pk_mul_f32 v[98:99], v[78:79], v[84:85] op_sel_hi:[1,0]
	v_pk_mul_f32 v[98:99], v[98:99], v[78:79]
	v_pk_fma_f32 v[98:99], v[98:99], v[78:79], v[78:79]
	v_pk_mul_f32 v[98:99], v[98:99], v[86:87] op_sel_hi:[1,0]
	v_pk_mul_f32 v[98:99], v[98:99], v[88:89] op_sel_hi:[1,0]
	v_exp_f32_e32 v96, v96
	v_exp_f32_e32 v97, v97
	v_exp_f32_e32 v98, v98
	v_exp_f32_e32 v99, v99
	v_pk_add_f32 v[96:97], v[96:97], v[90:91] op_sel_hi:[1,0]
	v_pk_add_f32 v[98:99], v[98:99], v[90:91] op_sel_hi:[1,0]
	v_rcp_f32_e32 v96, v96
	v_rcp_f32_e32 v97, v97
	v_rcp_f32_e32 v98, v98
	v_rcp_f32_e32 v99, v99
	v_pk_fma_f32 v[96:97], v[96:97], v[92:93], v[90:91] op_sel_hi:[1,0,0]
	v_pk_fma_f32 v[98:99], v[98:99], v[92:93], v[90:91] op_sel_hi:[1,0,0]
	v_pk_add_f32 v[96:97], v[96:97], v[90:91] op_sel_hi:[1,0]
	v_pk_mul_f32 v[76:77], v[76:77], v[94:95] op_sel_hi:[1,0]
	v_pk_mul_f32 v[76:77], v[76:77], v[96:97]
	v_pk_add_f32 v[98:99], v[98:99], v[90:91] op_sel_hi:[1,0]
	v_pk_mul_f32 v[78:79], v[78:79], v[94:95] op_sel_hi:[1,0]
	v_pk_mul_f32 v[78:79], v[78:79], v[98:99]
	v_pk_mul_f32 v[96:97], v[80:81], v[84:85] op_sel_hi:[1,0]
	v_pk_mul_f32 v[96:97], v[96:97], v[80:81]
	v_pk_fma_f32 v[96:97], v[96:97], v[80:81], v[80:81]
	v_pk_mul_f32 v[96:97], v[96:97], v[86:87] op_sel_hi:[1,0]
	v_pk_mul_f32 v[96:97], v[96:97], v[88:89] op_sel_hi:[1,0]
	v_pk_mul_f32 v[98:99], v[82:83], v[84:85] op_sel_hi:[1,0]
	v_pk_mul_f32 v[98:99], v[98:99], v[82:83]
	v_pk_fma_f32 v[98:99], v[98:99], v[82:83], v[82:83]
	v_pk_mul_f32 v[98:99], v[98:99], v[86:87] op_sel_hi:[1,0]
	v_pk_mul_f32 v[98:99], v[98:99], v[88:89] op_sel_hi:[1,0]
	v_exp_f32_e32 v96, v96
	v_exp_f32_e32 v97, v97
	v_exp_f32_e32 v98, v98
	v_exp_f32_e32 v99, v99
	v_pk_add_f32 v[96:97], v[96:97], v[90:91] op_sel_hi:[1,0]
	v_pk_add_f32 v[98:99], v[98:99], v[90:91] op_sel_hi:[1,0]
	v_rcp_f32_e32 v96, v96
	v_rcp_f32_e32 v97, v97
	v_rcp_f32_e32 v98, v98
	v_rcp_f32_e32 v99, v99
	v_pk_fma_f32 v[96:97], v[96:97], v[92:93], v[90:91] op_sel_hi:[1,0,0]
	v_pk_fma_f32 v[98:99], v[98:99], v[92:93], v[90:91] op_sel_hi:[1,0,0]
	v_pk_add_f32 v[96:97], v[96:97], v[90:91] op_sel_hi:[1,0]
	v_pk_mul_f32 v[80:81], v[80:81], v[94:95] op_sel_hi:[1,0]
	v_pk_mul_f32 v[80:81], v[80:81], v[96:97]
	v_pk_add_f32 v[98:99], v[98:99], v[90:91] op_sel_hi:[1,0]
	v_pk_mul_f32 v[82:83], v[82:83], v[94:95] op_sel_hi:[1,0]
	v_pk_mul_f32 v[82:83], v[82:83], v[98:99]
	v_lshl_add_u64 v[96:97], s[60:61], 0, v[104:105]
	s_mov_b32 s2, 0x19400000
	s_mov_b32 s3, 0
	v_lshl_add_u64 v[96:97], v[96:97], 0, s[2:3]
	s_mov_b32 s2, 0x1000
	v_fma_f32 v1, v120, v1, v118
	v_mul_f32_e32 v72, v76, v1
	v_bfe_u32 v73, v72, 16, 1
	v_add3_u32 v72, v72, v73, s84
	global_store_short_d16_hi v[96:97], v72, off offset:1024
	v_and_b32_e32 v72, 0xffff0000, v72
	v_mul_f32_e32 v72, v72, v72
	ds_write_b32 v144, v72
	v_fma_f32 v1, v121, v1, v119
	v_mul_f32_e32 v72, v77, v1
	v_bfe_u32 v73, v72, 16, 1
	v_add3_u32 v72, v72, v73, s84
	global_store_short_d16_hi v[96:97], v72, off offset:3072
	v_and_b32_e32 v72, 0xffff0000, v72
	v_mul_f32_e32 v72, v72, v72
	ds_write_b32 v146, v72
	v_lshl_add_u64 v[96:97], v[96:97], 0, s[2:3]
	v_fma_f32 v1, v116, v1, v114
	v_mul_f32_e32 v72, v78, v1
	v_bfe_u32 v73, v72, 16, 1
	v_add3_u32 v72, v72, v73, s84
	global_store_short_d16_hi v[96:97], v72, off offset:1024
	v_and_b32_e32 v72, 0xffff0000, v72
	v_mul_f32_e32 v72, v72, v72
	ds_write_b32 v146, v72 offset:132
	v_fma_f32 v1, v117, v1, v115
	v_mul_f32_e32 v72, v79, v1
	v_bfe_u32 v73, v72, 16, 1
	v_add3_u32 v72, v72, v73, s84
	global_store_short_d16_hi v[96:97], v72, off offset:3072
	v_and_b32_e32 v72, 0xffff0000, v72
	v_mul_f32_e32 v72, v72, v72
	ds_write_b32 v146, v72 offset:264
	v_lshl_add_u64 v[96:97], v[96:97], 0, s[2:3]
	v_fma_f32 v1, v112, v1, v110
	v_mul_f32_e32 v72, v80, v1
	v_bfe_u32 v73, v72, 16, 1
	v_add3_u32 v72, v72, v73, s84
	global_store_short_d16_hi v[96:97], v72, off offset:1024
	v_and_b32_e32 v72, 0xffff0000, v72
	v_mul_f32_e32 v72, v72, v72
	ds_write_b32 v146, v72 offset:396
	v_fma_f32 v1, v113, v1, v111
	v_mul_f32_e32 v72, v81, v1
	v_bfe_u32 v73, v72, 16, 1
	v_add3_u32 v72, v72, v73, s84
	global_store_short_d16_hi v[96:97], v72, off offset:3072
	v_and_b32_e32 v72, 0xffff0000, v72
	v_mul_f32_e32 v72, v72, v72
	ds_write_b32 v146, v72 offset:528
	v_lshl_add_u64 v[96:97], v[96:97], 0, s[2:3]
	v_fma_f32 v1, v108, v1, v2
	v_mul_f32_e32 v72, v82, v1
	v_bfe_u32 v73, v72, 16, 1
	v_add3_u32 v72, v72, v73, s84
	global_store_short_d16_hi v[96:97], v72, off offset:1024
	v_and_b32_e32 v72, 0xffff0000, v72
	v_mul_f32_e32 v72, v72, v72
	ds_write_b32 v146, v72 offset:660
	v_fma_f32 v3, v109, v1, v3
	v_mul_f32_e32 v72, v83, v3
	v_bfe_u32 v73, v72, 16, 1
	v_add3_u32 v72, v72, v73, s84
	global_store_short_d16_hi v[96:97], v72, off offset:3072
	v_and_b32_e32 v72, 0xffff0000, v72
	v_mul_f32_e32 v72, v72, v72
	ds_write_b32 v146, v72 offset:792
	s_waitcnt lgkmcnt(0)
	s_barrier
; __device__ __forceinline__ void rglru_unit(LAS unsigned char* lds, int unit, const bf16* PBp, bf16* MGp, float* SSQRp, const float* cw, const float* cbias, const float* wa, const float* ba, const float* wx, const float* bxp, const float* lam) {
;     ...
;         __syncthreads();
;         if (ss == 15) HIN[sc] = h;
;         if (tid < 128) { float sq = 0.f;
; #pragma unroll
;             for (int c2 = 0; c2 < 32; ++c2) sq += YSQ[tid * 33 + c2];
;             SSQRp[(rowb + t0 + tid) * 16 + g * 2 + hf] = sq; }
	s_and_saveexec_b64 s[2:3], s[4:5]
	ds_write_b32 v135, v3
	s_or_b64 exec, exec, s[2:3]
	s_and_saveexec_b64 s[2:3], s[6:7]
	s_cbranch_execz .LBB0_433
	ds_read2_b32 v[76:77], v153 offset1:1
	ds_read2_b32 v[78:79], v153 offset0:2 offset1:3
	ds_read2_b32 v[80:81], v153 offset0:4 offset1:5
	ds_read2_b32 v[82:83], v153 offset0:6 offset1:7
	ds_read2_b32 v[84:85], v153 offset0:8 offset1:9
	ds_read2_b32 v[86:87], v153 offset0:10 offset1:11
	ds_read2_b32 v[88:89], v153 offset0:12 offset1:13
	ds_read2_b32 v[90:91], v153 offset0:14 offset1:15
	ds_read2_b32 v[92:93], v153 offset0:16 offset1:17
	ds_read2_b32 v[94:95], v153 offset0:18 offset1:19
	ds_read2_b32 v[96:97], v153 offset0:20 offset1:21
	ds_read2_b32 v[98:99], v153 offset0:22 offset1:23
	s_waitcnt lgkmcnt(4)
	ds_read2_b32 v[108:109], v153 offset0:24 offset1:25
	ds_read2_b32 v[110:111], v153 offset0:26 offset1:27
	ds_read2_b32 v[112:113], v153 offset0:28 offset1:29
	ds_read2_b32 v[114:115], v153 offset0:30 offset1:31
	v_add_f32_e32 v1, 0, v76
	v_add_f32_e32 v1, v1, v77
	v_add_f32_e32 v1, v1, v78
	v_add_f32_e32 v1, v1, v79
	v_add_f32_e32 v1, v1, v80
	v_add_f32_e32 v1, v1, v81
	v_add_f32_e32 v1, v1, v82
	v_add_f32_e32 v1, v1, v83
	v_add_f32_e32 v1, v1, v84
	v_add_f32_e32 v1, v1, v85
	v_add_f32_e32 v1, v1, v86
	v_add_f32_e32 v1, v1, v87
	v_add_f32_e32 v1, v1, v88
	v_add_f32_e32 v1, v1, v89
	v_add_f32_e32 v1, v1, v90
	v_add_f32_e32 v1, v1, v91
	s_waitcnt lgkmcnt(0)
	v_add_f32_e32 v1, v1, v92
	v_add_f32_e32 v1, v1, v93
	v_add_f32_e32 v1, v1, v94
	v_add_f32_e32 v1, v1, v95
	v_add_f32_e32 v1, v1, v96
	v_add_f32_e32 v1, v1, v97
	v_add_f32_e32 v1, v1, v98
	v_add_f32_e32 v1, v1, v99
	v_add_f32_e32 v1, v1, v108
	v_add_f32_e32 v1, v1, v109
	v_add_f32_e32 v1, v1, v110
	v_add_f32_e32 v1, v1, v111
	v_add_f32_e32 v1, v1, v112
	v_add_f32_e32 v1, v1, v113
	v_add_f32_e32 v1, v1, v114
	v_add_f32_e32 v1, v1, v115
	v_lshl_add_u64 v[2:3], s[60:61], 0, v[102:103]
	global_store_dword v[2:3], v1, off
	s_branch .LBB0_433
